# gemm_in generic epilogue: coalesced z stores via lane transpose (ds_bpermute)
# speedup vs baseline: 1.0285x; 1.0107x over previous
; template <int EPI>
; DI void gemm_epilogue(const Params& p, int layer, f32x4 (&acc)[2][2][4][2], int brow, int bcol, int pn, int wr, int wc,
;                       int fr, int fq, char* smem, int ksplit = -1) {
;     ...
;   if (EPI == EPI_IN) {
;     u16* Z = p.z;
;     const bool latent = brow < NLAT;
;     if (pn == 9 || pn == 10) {
;     ...
;     } else {
;       const float sc = (pn == 0 || pn == 6 || pn == 11) ? 0.125f : 1.f;
;       const bool dosilu = (pn == 0);
; #pragma unroll
.LBB0_155:
	v_mov_b32_e32 v0, v234
	s_lshl_b32 s22, s23, 8
	s_lshl_b32 s25, s24, 8
	s_add_i32 s0, s24, -9
	s_cmp_gt_u32 s0, 1
	v_and_b32_e32 v160, 15, v0
	v_bfe_u32 v161, v0, 4, 2
	s_mov_b64 s[0:1], -1
	s_cbranch_scc0 .LBB0_227
	v_bfe_u32 v160, v234, 2, 4
	v_and_b32_e32 v161, 3, v234
	v_lshl_or_b32 v200, v161, 4, v160
	v_lshlrev_b32_e32 v200, 2, v200
	s_cmp_lt_i32 s24, 6
	s_cbranch_scc1 .LBB0_158
	s_cmp_lg_u32 s24, 6
	s_cselect_b64 s[0:1], -1, 0
	s_cbranch_execz .LBB0_159
	s_branch .LBB0_160

; DI float siluf(float x) { return x * __builtin_amdgcn_rcpf(1.f + __expf(-x)); }
; template <int EPI>
; DI void gemm_epilogue(const Params& p, int layer, f32x4 (&acc)[2][2][4][2], int brow, int bcol, int pn, int wr, int wc,
;                       int fr, int fq, char* smem, int ksplit = -1) {
;     ...
; #pragma unroll
;       for (int ai = 0; ai < 2; ++ai)
; #pragma unroll
;         for (int m = 0; m < 4; ++m) {
;           __builtin_amdgcn_sched_barrier(0);
;           const int row = brow + ai * 128 + wr * 64 + m * 16 + fr;
; #pragma unroll
;           for (int bj = 0; bj < 2; ++bj) {
;             u32x4 o;
; #pragma unroll
;             for (int n = 0; n < 2; ++n) {
;               f32x4 v = acc[ai][bj][m][n];
;               if (dosilu) {
; #pragma unroll
;                 for (int j = 0; j < 4; ++j) v[j] = siluf(v[j]);
;               }
;               v = v * sc;
;               o[2 * n] = pk_bf16(v[0], v[1]);
;               o[2 * n + 1] = pk_bf16(v[2], v[3]);
;             }
;             *(u32x4*)(Z + (size_t)row * ZW + bcol + bj * 128 + wc * 32 + fq * 8) = o;
;           }
.LBB0_168:
	s_add_i32 s0, s22, s14
	v_or_b32_e32 v162, s0, v160
	s_lshl_b32 s0, s25, 1
	s_add_u32 s0, s19, s0
	s_addc_u32 s1, s20, 0
	v_lshlrev_b32_e32 v0, 4, v161
	v_lshl_add_u64 v[138:139], s[0:1], 0, v[0:1]
	v_mad_i64_i32 v[140:141], s[0:1], v162, s79, v[138:139]
	ds_bpermute_b32 v130, v200, v130
	ds_bpermute_b32 v131, v200, v131
	ds_bpermute_b32 v132, v200, v132
	ds_bpermute_b32 v133, v200, v133
	s_waitcnt lgkmcnt(0)
	global_store_dwordx4 v[140:141], v[130:133], off
	v_cndmask_b32_e64 v0, 0, 1, s[4:5]
	v_cmp_ne_u32_e64 s[0:1], 1, v0
	v_mov_b64_e32 v[132:133], v[116:117]
	s_andn2_b64 vcc, exec, s[4:5]
	v_mov_b64_e32 v[130:131], v[114:115]
	s_cbranch_vccnz .LBB0_170
	v_mul_f32_e32 v0, 0xbfb8aa3b, v114
	v_exp_f32_e32 v0, v0
	v_mul_f32_e32 v130, 0xbfb8aa3b, v115
	v_mul_f32_e32 v131, 0xbfb8aa3b, v116
	v_exp_f32_e32 v132, v130
	v_add_f32_e32 v0, 1.0, v0
	v_rcp_f32_e32 v130, v0
	v_exp_f32_e32 v0, v131
	v_mul_f32_e32 v131, 0xbfb8aa3b, v117
	v_exp_f32_e32 v131, v131
	v_add_f32_e32 v156, 1.0, v132
	v_add_f32_e32 v0, 1.0, v0
	v_rcp_f32_e32 v132, v0
	v_add_f32_e32 v0, 1.0, v131
	v_rcp_f32_e32 v133, v0
	v_rcp_f32_e32 v131, v156
	v_pk_mul_f32 v[132:133], v[116:117], v[132:133]
	v_pk_mul_f32 v[130:131], v[114:115], v[130:131]
.LBB0_170:
	v_mov_b32_e32 v156, v154
	v_mov_b32_e32 v157, v154
	v_pk_mul_f32 v[136:137], v[156:157], v[136:137]
	v_pk_mul_f32 v[134:135], v[154:155], v[134:135]
	v_pk_mul_f32 v[132:133], v[156:157], v[132:133]
	v_pk_mul_f32 v[130:131], v[154:155], v[130:131]
	v_cvt_pk_bf16_f32 v134, v134, v135
	v_cvt_pk_bf16_f32 v135, v136, v137
	v_cvt_pk_bf16_f32 v136, v130, v131
	v_cvt_pk_bf16_f32 v137, v132, v133
	ds_bpermute_b32 v134, v200, v134
	ds_bpermute_b32 v135, v200, v135
	ds_bpermute_b32 v136, v200, v136
	ds_bpermute_b32 v137, v200, v137
	s_waitcnt lgkmcnt(0)
	global_store_dwordx4 v[140:141], v[134:137], off offset:256
	v_mov_b64_e32 v[132:133], v[112:113]
	s_and_b64 vcc, exec, s[0:1]
	v_mov_b64_e32 v[130:131], v[110:111]
	s_cbranch_vccnz .LBB0_172
	v_mul_f32_e32 v0, 0xbfb8aa3b, v110
	v_exp_f32_e32 v0, v0
	v_mul_f32_e32 v130, 0xbfb8aa3b, v111
	v_mul_f32_e32 v131, 0xbfb8aa3b, v112
	v_exp_f32_e32 v132, v130
	v_add_f32_e32 v0, 1.0, v0
	v_rcp_f32_e32 v130, v0
	v_exp_f32_e32 v0, v131
	v_mul_f32_e32 v131, 0xbfb8aa3b, v113
	v_exp_f32_e32 v131, v131
	v_add_f32_e32 v134, 1.0, v132
	v_add_f32_e32 v0, 1.0, v0
	v_rcp_f32_e32 v132, v0
	v_add_f32_e32 v0, 1.0, v131
	v_rcp_f32_e32 v133, v0
	v_rcp_f32_e32 v131, v134
	v_pk_mul_f32 v[132:133], v[112:113], v[132:133]
	v_pk_mul_f32 v[130:131], v[110:111], v[130:131]

; DI float siluf(float x) { return x * __builtin_amdgcn_rcpf(1.f + __expf(-x)); }
; template <int EPI>
; DI void gemm_epilogue(const Params& p, int layer, f32x4 (&acc)[2][2][4][2], int brow, int bcol, int pn, int wr, int wc,
;                       int fr, int fq, char* smem, int ksplit = -1) {
;     ...
; #pragma unroll
;       for (int ai = 0; ai < 2; ++ai)
; #pragma unroll
;         for (int m = 0; m < 4; ++m) {
;           __builtin_amdgcn_sched_barrier(0);
;           const int row = brow + ai * 128 + wr * 64 + m * 16 + fr;
; #pragma unroll
;           for (int bj = 0; bj < 2; ++bj) {
;             u32x4 o;
; #pragma unroll
;             for (int n = 0; n < 2; ++n) {
;               f32x4 v = acc[ai][bj][m][n];
;               if (dosilu) {
; #pragma unroll
;                 for (int j = 0; j < 4; ++j) v[j] = siluf(v[j]);
;               }
;               v = v * sc;
;               o[2 * n] = pk_bf16(v[0], v[1]);
;               o[2 * n + 1] = pk_bf16(v[2], v[3]);
;             }
;             *(u32x4*)(Z + (size_t)row * ZW + bcol + bj * 128 + wc * 32 + fq * 8) = o;
;           }
.LBB0_176:
	v_or_b32_e32 v0, 16, v162
	v_mad_i64_i32 v[156:157], s[4:5], v0, s79, v[138:139]
	ds_bpermute_b32 v130, v200, v130
	ds_bpermute_b32 v131, v200, v131
	ds_bpermute_b32 v132, v200, v132
	ds_bpermute_b32 v133, v200, v133
	s_waitcnt lgkmcnt(0)
	global_store_dwordx4 v[156:157], v[130:133], off
	s_and_b64 vcc, exec, s[0:1]
	s_nop 0
	v_mov_b64_e32 v[132:133], v[100:101]
	v_mov_b64_e32 v[130:131], v[98:99]
	s_cbranch_vccnz .LBB0_178
	v_mul_f32_e32 v0, 0xbfb8aa3b, v98
	v_exp_f32_e32 v0, v0
	v_mul_f32_e32 v130, 0xbfb8aa3b, v99
	v_mul_f32_e32 v131, 0xbfb8aa3b, v100
	v_exp_f32_e32 v132, v130
	v_add_f32_e32 v0, 1.0, v0
	v_rcp_f32_e32 v130, v0
	v_exp_f32_e32 v0, v131
	v_mul_f32_e32 v131, 0xbfb8aa3b, v101
	v_exp_f32_e32 v131, v131
	v_add_f32_e32 v140, 1.0, v132
	v_add_f32_e32 v0, 1.0, v0
	v_rcp_f32_e32 v132, v0
	v_add_f32_e32 v0, 1.0, v131
	v_rcp_f32_e32 v133, v0
	v_rcp_f32_e32 v131, v140
	v_pk_mul_f32 v[132:133], v[100:101], v[132:133]
	v_pk_mul_f32 v[130:131], v[98:99], v[130:131]
.LBB0_178:
	v_mov_b32_e32 v140, v154
	v_mov_b32_e32 v141, v154
	v_pk_mul_f32 v[136:137], v[140:141], v[136:137]
	v_pk_mul_f32 v[134:135], v[154:155], v[134:135]
	v_pk_mul_f32 v[132:133], v[140:141], v[132:133]
	v_pk_mul_f32 v[130:131], v[154:155], v[130:131]
	v_cvt_pk_bf16_f32 v134, v134, v135
	v_cvt_pk_bf16_f32 v135, v136, v137
	v_cvt_pk_bf16_f32 v136, v130, v131
	v_cvt_pk_bf16_f32 v137, v132, v133
	ds_bpermute_b32 v134, v200, v134
	ds_bpermute_b32 v135, v200, v135
	ds_bpermute_b32 v136, v200, v136
	ds_bpermute_b32 v137, v200, v137
	s_waitcnt lgkmcnt(0)
	global_store_dwordx4 v[156:157], v[134:137], off offset:256
	v_mov_b64_e32 v[132:133], v[96:97]
	s_and_b64 vcc, exec, s[0:1]
	v_mov_b64_e32 v[130:131], v[94:95]
	s_cbranch_vccnz .LBB0_180
	v_mul_f32_e32 v0, 0xbfb8aa3b, v94
	v_exp_f32_e32 v0, v0
	v_mul_f32_e32 v130, 0xbfb8aa3b, v95
	v_mul_f32_e32 v131, 0xbfb8aa3b, v96
	v_exp_f32_e32 v132, v130
	v_add_f32_e32 v0, 1.0, v0
	v_rcp_f32_e32 v130, v0
	v_exp_f32_e32 v0, v131
	v_mul_f32_e32 v131, 0xbfb8aa3b, v97
	v_exp_f32_e32 v131, v131
	v_add_f32_e32 v134, 1.0, v132
	v_add_f32_e32 v0, 1.0, v0
	v_rcp_f32_e32 v132, v0
	v_add_f32_e32 v0, 1.0, v131
	v_rcp_f32_e32 v133, v0
	v_rcp_f32_e32 v131, v134
	v_pk_mul_f32 v[132:133], v[96:97], v[132:133]
	v_pk_mul_f32 v[130:131], v[94:95], v[130:131]

; DI float siluf(float x) { return x * __builtin_amdgcn_rcpf(1.f + __expf(-x)); }
; template <int EPI>
; DI void gemm_epilogue(const Params& p, int layer, f32x4 (&acc)[2][2][4][2], int brow, int bcol, int pn, int wr, int wc,
;                       int fr, int fq, char* smem, int ksplit = -1) {
;     ...
; #pragma unroll
;       for (int ai = 0; ai < 2; ++ai)
; #pragma unroll
;         for (int m = 0; m < 4; ++m) {
;           __builtin_amdgcn_sched_barrier(0);
;           const int row = brow + ai * 128 + wr * 64 + m * 16 + fr;
; #pragma unroll
;           for (int bj = 0; bj < 2; ++bj) {
;             u32x4 o;
; #pragma unroll
;             for (int n = 0; n < 2; ++n) {
;               f32x4 v = acc[ai][bj][m][n];
;               if (dosilu) {
; #pragma unroll
;                 for (int j = 0; j < 4; ++j) v[j] = siluf(v[j]);
;               }
;               v = v * sc;
;               o[2 * n] = pk_bf16(v[0], v[1]);
;               o[2 * n + 1] = pk_bf16(v[2], v[3]);
;             }
;             *(u32x4*)(Z + (size_t)row * ZW + bcol + bj * 128 + wc * 32 + fq * 8) = o;
;           }
.LBB0_184:
	v_or_b32_e32 v0, 32, v162
	v_mad_i64_i32 v[156:157], s[4:5], v0, s79, v[138:139]
	ds_bpermute_b32 v130, v200, v130
	ds_bpermute_b32 v131, v200, v131
	ds_bpermute_b32 v132, v200, v132
	ds_bpermute_b32 v133, v200, v133
	s_waitcnt lgkmcnt(0)
	global_store_dwordx4 v[156:157], v[130:133], off
	s_and_b64 vcc, exec, s[0:1]
	s_nop 0
	v_mov_b64_e32 v[132:133], v[84:85]
	v_mov_b64_e32 v[130:131], v[82:83]
	s_cbranch_vccnz .LBB0_186
	v_mul_f32_e32 v0, 0xbfb8aa3b, v82
	v_exp_f32_e32 v0, v0
	v_mul_f32_e32 v130, 0xbfb8aa3b, v83
	v_mul_f32_e32 v131, 0xbfb8aa3b, v84
	v_exp_f32_e32 v132, v130
	v_add_f32_e32 v0, 1.0, v0
	v_rcp_f32_e32 v130, v0
	v_exp_f32_e32 v0, v131
	v_mul_f32_e32 v131, 0xbfb8aa3b, v85
	v_exp_f32_e32 v131, v131
	v_add_f32_e32 v140, 1.0, v132
	v_add_f32_e32 v0, 1.0, v0
	v_rcp_f32_e32 v132, v0
	v_add_f32_e32 v0, 1.0, v131
	v_rcp_f32_e32 v133, v0
	v_rcp_f32_e32 v131, v140
	v_pk_mul_f32 v[132:133], v[84:85], v[132:133]
	v_pk_mul_f32 v[130:131], v[82:83], v[130:131]
.LBB0_186:
	v_mov_b32_e32 v140, v154
	v_mov_b32_e32 v141, v154
	v_pk_mul_f32 v[136:137], v[140:141], v[136:137]
	v_pk_mul_f32 v[134:135], v[154:155], v[134:135]
	v_pk_mul_f32 v[132:133], v[140:141], v[132:133]
	v_pk_mul_f32 v[130:131], v[154:155], v[130:131]
	v_cvt_pk_bf16_f32 v134, v134, v135
	v_cvt_pk_bf16_f32 v135, v136, v137
	v_cvt_pk_bf16_f32 v136, v130, v131
	v_cvt_pk_bf16_f32 v137, v132, v133
	ds_bpermute_b32 v134, v200, v134
	ds_bpermute_b32 v135, v200, v135
	ds_bpermute_b32 v136, v200, v136
	ds_bpermute_b32 v137, v200, v137
	s_waitcnt lgkmcnt(0)
	global_store_dwordx4 v[156:157], v[134:137], off offset:256
	v_mov_b64_e32 v[132:133], v[80:81]
	s_and_b64 vcc, exec, s[0:1]
	v_mov_b64_e32 v[130:131], v[78:79]
	s_cbranch_vccnz .LBB0_188
	v_mul_f32_e32 v0, 0xbfb8aa3b, v78
	v_exp_f32_e32 v0, v0
	v_mul_f32_e32 v130, 0xbfb8aa3b, v79
	v_mul_f32_e32 v131, 0xbfb8aa3b, v80
	v_exp_f32_e32 v132, v130
	v_add_f32_e32 v0, 1.0, v0
	v_rcp_f32_e32 v130, v0
	v_exp_f32_e32 v0, v131
	v_mul_f32_e32 v131, 0xbfb8aa3b, v81
	v_exp_f32_e32 v131, v131
	v_add_f32_e32 v134, 1.0, v132
	v_add_f32_e32 v0, 1.0, v0
	v_rcp_f32_e32 v132, v0
	v_add_f32_e32 v0, 1.0, v131
	v_rcp_f32_e32 v133, v0
	v_rcp_f32_e32 v131, v134
	v_pk_mul_f32 v[132:133], v[80:81], v[132:133]
	v_pk_mul_f32 v[130:131], v[78:79], v[130:131]

; DI float siluf(float x) { return x * __builtin_amdgcn_rcpf(1.f + __expf(-x)); }
; template <int EPI>
; DI void gemm_epilogue(const Params& p, int layer, f32x4 (&acc)[2][2][4][2], int brow, int bcol, int pn, int wr, int wc,
;                       int fr, int fq, char* smem, int ksplit = -1) {
;     ...
; #pragma unroll
;       for (int ai = 0; ai < 2; ++ai)
; #pragma unroll
;         for (int m = 0; m < 4; ++m) {
;           __builtin_amdgcn_sched_barrier(0);
;           const int row = brow + ai * 128 + wr * 64 + m * 16 + fr;
; #pragma unroll
;           for (int bj = 0; bj < 2; ++bj) {
;             u32x4 o;
; #pragma unroll
;             for (int n = 0; n < 2; ++n) {
;               f32x4 v = acc[ai][bj][m][n];
;               if (dosilu) {
; #pragma unroll
;                 for (int j = 0; j < 4; ++j) v[j] = siluf(v[j]);
;               }
;               v = v * sc;
;               o[2 * n] = pk_bf16(v[0], v[1]);
;               o[2 * n + 1] = pk_bf16(v[2], v[3]);
;             }
;             *(u32x4*)(Z + (size_t)row * ZW + bcol + bj * 128 + wc * 32 + fq * 8) = o;
;           }
.LBB0_192:
	v_or_b32_e32 v0, 48, v162
	v_mad_i64_i32 v[156:157], s[4:5], v0, s79, v[138:139]
	ds_bpermute_b32 v130, v200, v130
	ds_bpermute_b32 v131, v200, v131
	ds_bpermute_b32 v132, v200, v132
	ds_bpermute_b32 v133, v200, v133
	s_waitcnt lgkmcnt(0)
	global_store_dwordx4 v[156:157], v[130:133], off
	s_and_b64 vcc, exec, s[0:1]
	s_nop 0
	v_mov_b64_e32 v[132:133], v[68:69]
	v_mov_b64_e32 v[130:131], v[66:67]
	s_cbranch_vccnz .LBB0_194
	v_mul_f32_e32 v0, 0xbfb8aa3b, v66
	v_exp_f32_e32 v0, v0
	v_mul_f32_e32 v130, 0xbfb8aa3b, v67
	v_mul_f32_e32 v131, 0xbfb8aa3b, v68
	v_exp_f32_e32 v132, v130
	v_add_f32_e32 v0, 1.0, v0
	v_rcp_f32_e32 v130, v0
	v_exp_f32_e32 v0, v131
	v_mul_f32_e32 v131, 0xbfb8aa3b, v69
	v_exp_f32_e32 v131, v131
	v_add_f32_e32 v140, 1.0, v132
	v_add_f32_e32 v0, 1.0, v0
	v_rcp_f32_e32 v132, v0
	v_add_f32_e32 v0, 1.0, v131
	v_rcp_f32_e32 v133, v0
	v_rcp_f32_e32 v131, v140
	v_pk_mul_f32 v[132:133], v[68:69], v[132:133]
	v_pk_mul_f32 v[130:131], v[66:67], v[130:131]
.LBB0_194:
	v_mov_b32_e32 v140, v154
	v_mov_b32_e32 v141, v154
	v_pk_mul_f32 v[136:137], v[140:141], v[136:137]
	v_pk_mul_f32 v[134:135], v[154:155], v[134:135]
	v_pk_mul_f32 v[132:133], v[140:141], v[132:133]
	v_pk_mul_f32 v[130:131], v[154:155], v[130:131]
	v_cvt_pk_bf16_f32 v134, v134, v135
	v_cvt_pk_bf16_f32 v135, v136, v137
	v_cvt_pk_bf16_f32 v136, v130, v131
	v_cvt_pk_bf16_f32 v137, v132, v133
	ds_bpermute_b32 v134, v200, v134
	ds_bpermute_b32 v135, v200, v135
	ds_bpermute_b32 v136, v200, v136
	ds_bpermute_b32 v137, v200, v137
	s_waitcnt lgkmcnt(0)
	global_store_dwordx4 v[156:157], v[134:137], off offset:256
	v_mov_b64_e32 v[132:133], v[64:65]
	s_and_b64 vcc, exec, s[0:1]
	v_mov_b64_e32 v[130:131], v[62:63]
	s_cbranch_vccnz .LBB0_196
	v_mul_f32_e32 v0, 0xbfb8aa3b, v62
	v_exp_f32_e32 v0, v0
	v_mul_f32_e32 v130, 0xbfb8aa3b, v63
	v_mul_f32_e32 v131, 0xbfb8aa3b, v64
	v_exp_f32_e32 v132, v130
	v_add_f32_e32 v0, 1.0, v0
	v_rcp_f32_e32 v130, v0
	v_exp_f32_e32 v0, v131
	v_mul_f32_e32 v131, 0xbfb8aa3b, v65
	v_exp_f32_e32 v131, v131
	v_add_f32_e32 v134, 1.0, v132
	v_add_f32_e32 v0, 1.0, v0
	v_rcp_f32_e32 v132, v0
	v_add_f32_e32 v0, 1.0, v131
	v_rcp_f32_e32 v133, v0
	v_rcp_f32_e32 v131, v134
	v_pk_mul_f32 v[132:133], v[64:65], v[132:133]
	v_pk_mul_f32 v[130:131], v[62:63], v[130:131]

; DI float siluf(float x) { return x * __builtin_amdgcn_rcpf(1.f + __expf(-x)); }
; template <int EPI>
; DI void gemm_epilogue(const Params& p, int layer, f32x4 (&acc)[2][2][4][2], int brow, int bcol, int pn, int wr, int wc,
;                       int fr, int fq, char* smem, int ksplit = -1) {
;     ...
; #pragma unroll
;       for (int ai = 0; ai < 2; ++ai)
; #pragma unroll
;         for (int m = 0; m < 4; ++m) {
;           __builtin_amdgcn_sched_barrier(0);
;           const int row = brow + ai * 128 + wr * 64 + m * 16 + fr;
; #pragma unroll
;           for (int bj = 0; bj < 2; ++bj) {
;             u32x4 o;
; #pragma unroll
;             for (int n = 0; n < 2; ++n) {
;               f32x4 v = acc[ai][bj][m][n];
;               if (dosilu) {
; #pragma unroll
;                 for (int j = 0; j < 4; ++j) v[j] = siluf(v[j]);
;               }
;               v = v * sc;
;               o[2 * n] = pk_bf16(v[0], v[1]);
;               o[2 * n + 1] = pk_bf16(v[2], v[3]);
;             }
;             *(u32x4*)(Z + (size_t)row * ZW + bcol + bj * 128 + wc * 32 + fq * 8) = o;
;           }
.LBB0_200:
	v_add_u32_e32 v0, 0x80, v162
	v_mad_i64_i32 v[156:157], s[4:5], v0, s79, v[138:139]
	ds_bpermute_b32 v130, v200, v130
	ds_bpermute_b32 v131, v200, v131
	ds_bpermute_b32 v132, v200, v132
	ds_bpermute_b32 v133, v200, v133
	s_waitcnt lgkmcnt(0)
	global_store_dwordx4 v[156:157], v[130:133], off
	s_and_b64 vcc, exec, s[0:1]
	s_nop 0
	v_mov_b64_e32 v[132:133], v[52:53]
	v_mov_b64_e32 v[130:131], v[50:51]
	s_cbranch_vccnz .LBB0_202
	v_mul_f32_e32 v0, 0xbfb8aa3b, v50
	v_exp_f32_e32 v0, v0
	v_mul_f32_e32 v130, 0xbfb8aa3b, v51
	v_mul_f32_e32 v131, 0xbfb8aa3b, v52
	v_exp_f32_e32 v132, v130
	v_add_f32_e32 v0, 1.0, v0
	v_rcp_f32_e32 v130, v0
	v_exp_f32_e32 v0, v131
	v_mul_f32_e32 v131, 0xbfb8aa3b, v53
	v_exp_f32_e32 v131, v131
	v_add_f32_e32 v140, 1.0, v132
	v_add_f32_e32 v0, 1.0, v0
	v_rcp_f32_e32 v132, v0
	v_add_f32_e32 v0, 1.0, v131
	v_rcp_f32_e32 v133, v0
	v_rcp_f32_e32 v131, v140
	v_pk_mul_f32 v[132:133], v[52:53], v[132:133]
	v_pk_mul_f32 v[130:131], v[50:51], v[130:131]
.LBB0_202:
	v_mov_b32_e32 v140, v154
	v_mov_b32_e32 v141, v154
	v_pk_mul_f32 v[136:137], v[140:141], v[136:137]
	v_pk_mul_f32 v[134:135], v[154:155], v[134:135]
	v_pk_mul_f32 v[132:133], v[140:141], v[132:133]
	v_pk_mul_f32 v[130:131], v[154:155], v[130:131]
	v_cvt_pk_bf16_f32 v134, v134, v135
	v_cvt_pk_bf16_f32 v135, v136, v137
	v_cvt_pk_bf16_f32 v136, v130, v131
	v_cvt_pk_bf16_f32 v137, v132, v133
	ds_bpermute_b32 v134, v200, v134
	ds_bpermute_b32 v135, v200, v135
	ds_bpermute_b32 v136, v200, v136
	ds_bpermute_b32 v137, v200, v137
	s_waitcnt lgkmcnt(0)
	global_store_dwordx4 v[156:157], v[134:137], off offset:256
	v_mov_b64_e32 v[132:133], v[48:49]
	s_and_b64 vcc, exec, s[0:1]
	v_mov_b64_e32 v[130:131], v[46:47]
	s_cbranch_vccnz .LBB0_204
	v_mul_f32_e32 v0, 0xbfb8aa3b, v46
	v_exp_f32_e32 v0, v0
	v_mul_f32_e32 v130, 0xbfb8aa3b, v47
	v_mul_f32_e32 v131, 0xbfb8aa3b, v48
	v_exp_f32_e32 v132, v130
	v_add_f32_e32 v0, 1.0, v0
	v_rcp_f32_e32 v130, v0
	v_exp_f32_e32 v0, v131
	v_mul_f32_e32 v131, 0xbfb8aa3b, v49
	v_exp_f32_e32 v131, v131
	v_add_f32_e32 v134, 1.0, v132
	v_add_f32_e32 v0, 1.0, v0
	v_rcp_f32_e32 v132, v0
	v_add_f32_e32 v0, 1.0, v131
	v_rcp_f32_e32 v133, v0
	v_rcp_f32_e32 v131, v134
	v_pk_mul_f32 v[132:133], v[48:49], v[132:133]
	v_pk_mul_f32 v[130:131], v[46:47], v[130:131]

; DI float siluf(float x) { return x * __builtin_amdgcn_rcpf(1.f + __expf(-x)); }
; template <int EPI>
; DI void gemm_epilogue(const Params& p, int layer, f32x4 (&acc)[2][2][4][2], int brow, int bcol, int pn, int wr, int wc,
;                       int fr, int fq, char* smem, int ksplit = -1) {
;     ...
; #pragma unroll
;       for (int ai = 0; ai < 2; ++ai)
; #pragma unroll
;         for (int m = 0; m < 4; ++m) {
;           __builtin_amdgcn_sched_barrier(0);
;           const int row = brow + ai * 128 + wr * 64 + m * 16 + fr;
; #pragma unroll
;           for (int bj = 0; bj < 2; ++bj) {
;             u32x4 o;
; #pragma unroll
;             for (int n = 0; n < 2; ++n) {
;               f32x4 v = acc[ai][bj][m][n];
;               if (dosilu) {
; #pragma unroll
;                 for (int j = 0; j < 4; ++j) v[j] = siluf(v[j]);
;               }
;               v = v * sc;
;               o[2 * n] = pk_bf16(v[0], v[1]);
;               o[2 * n + 1] = pk_bf16(v[2], v[3]);
;             }
;             *(u32x4*)(Z + (size_t)row * ZW + bcol + bj * 128 + wc * 32 + fq * 8) = o;
;           }
.LBB0_208:
	v_add_u32_e32 v0, 0x90, v162
	v_mad_i64_i32 v[156:157], s[4:5], v0, s79, v[138:139]
	ds_bpermute_b32 v130, v200, v130
	ds_bpermute_b32 v131, v200, v131
	ds_bpermute_b32 v132, v200, v132
	ds_bpermute_b32 v133, v200, v133
	s_waitcnt lgkmcnt(0)
	global_store_dwordx4 v[156:157], v[130:133], off
	s_and_b64 vcc, exec, s[0:1]
	s_nop 0
	v_mov_b64_e32 v[132:133], v[36:37]
	v_mov_b64_e32 v[130:131], v[34:35]
	s_cbranch_vccnz .LBB0_210
	v_mul_f32_e32 v0, 0xbfb8aa3b, v34
	v_exp_f32_e32 v0, v0
	v_mul_f32_e32 v130, 0xbfb8aa3b, v35
	v_mul_f32_e32 v131, 0xbfb8aa3b, v36
	v_exp_f32_e32 v132, v130
	v_add_f32_e32 v0, 1.0, v0
	v_rcp_f32_e32 v130, v0
	v_exp_f32_e32 v0, v131
	v_mul_f32_e32 v131, 0xbfb8aa3b, v37
	v_exp_f32_e32 v131, v131
	v_add_f32_e32 v140, 1.0, v132
	v_add_f32_e32 v0, 1.0, v0
	v_rcp_f32_e32 v132, v0
	v_add_f32_e32 v0, 1.0, v131
	v_rcp_f32_e32 v133, v0
	v_rcp_f32_e32 v131, v140
	v_pk_mul_f32 v[132:133], v[36:37], v[132:133]
	v_pk_mul_f32 v[130:131], v[34:35], v[130:131]
.LBB0_210:
	v_mov_b32_e32 v140, v154
	v_mov_b32_e32 v141, v154
	v_pk_mul_f32 v[136:137], v[140:141], v[136:137]
	v_pk_mul_f32 v[134:135], v[154:155], v[134:135]
	v_pk_mul_f32 v[132:133], v[140:141], v[132:133]
	v_pk_mul_f32 v[130:131], v[154:155], v[130:131]
	v_cvt_pk_bf16_f32 v134, v134, v135
	v_cvt_pk_bf16_f32 v135, v136, v137
	v_cvt_pk_bf16_f32 v136, v130, v131
	v_cvt_pk_bf16_f32 v137, v132, v133
	ds_bpermute_b32 v134, v200, v134
	ds_bpermute_b32 v135, v200, v135
	ds_bpermute_b32 v136, v200, v136
	ds_bpermute_b32 v137, v200, v137
	s_waitcnt lgkmcnt(0)
	global_store_dwordx4 v[156:157], v[134:137], off offset:256
	v_mov_b64_e32 v[132:133], v[32:33]
	s_and_b64 vcc, exec, s[0:1]
	v_mov_b64_e32 v[130:131], v[30:31]
	s_cbranch_vccnz .LBB0_212
	v_mul_f32_e32 v0, 0xbfb8aa3b, v30
	v_exp_f32_e32 v0, v0
	v_mul_f32_e32 v130, 0xbfb8aa3b, v31
	v_mul_f32_e32 v131, 0xbfb8aa3b, v32
	v_exp_f32_e32 v132, v130
	v_add_f32_e32 v0, 1.0, v0
	v_rcp_f32_e32 v130, v0
	v_exp_f32_e32 v0, v131
	v_mul_f32_e32 v131, 0xbfb8aa3b, v33
	v_exp_f32_e32 v131, v131
	v_add_f32_e32 v134, 1.0, v132
	v_add_f32_e32 v0, 1.0, v0
	v_rcp_f32_e32 v132, v0
	v_add_f32_e32 v0, 1.0, v131
	v_rcp_f32_e32 v133, v0
	v_rcp_f32_e32 v131, v134
	v_pk_mul_f32 v[132:133], v[32:33], v[132:133]
	v_pk_mul_f32 v[130:131], v[30:31], v[130:131]

; DI float siluf(float x) { return x * __builtin_amdgcn_rcpf(1.f + __expf(-x)); }
; template <int EPI>
; DI void gemm_epilogue(const Params& p, int layer, f32x4 (&acc)[2][2][4][2], int brow, int bcol, int pn, int wr, int wc,
;                       int fr, int fq, char* smem, int ksplit = -1) {
;     ...
; #pragma unroll
;       for (int ai = 0; ai < 2; ++ai)
; #pragma unroll
;         for (int m = 0; m < 4; ++m) {
;           __builtin_amdgcn_sched_barrier(0);
;           const int row = brow + ai * 128 + wr * 64 + m * 16 + fr;
; #pragma unroll
;           for (int bj = 0; bj < 2; ++bj) {
;             u32x4 o;
; #pragma unroll
;             for (int n = 0; n < 2; ++n) {
;               f32x4 v = acc[ai][bj][m][n];
;               if (dosilu) {
; #pragma unroll
;                 for (int j = 0; j < 4; ++j) v[j] = siluf(v[j]);
;               }
;               v = v * sc;
;               o[2 * n] = pk_bf16(v[0], v[1]);
;               o[2 * n + 1] = pk_bf16(v[2], v[3]);
;             }
;             *(u32x4*)(Z + (size_t)row * ZW + bcol + bj * 128 + wc * 32 + fq * 8) = o;
;           }
.LBB0_216:
	v_add_u32_e32 v0, 0xa0, v162
	v_mad_i64_i32 v[156:157], s[4:5], v0, s79, v[138:139]
	ds_bpermute_b32 v130, v200, v130
	ds_bpermute_b32 v131, v200, v131
	ds_bpermute_b32 v132, v200, v132
	ds_bpermute_b32 v133, v200, v133
	s_waitcnt lgkmcnt(0)
	global_store_dwordx4 v[156:157], v[130:133], off
	s_and_b64 vcc, exec, s[0:1]
	s_nop 0
	v_mov_b64_e32 v[132:133], v[20:21]
	v_mov_b64_e32 v[130:131], v[18:19]
	s_cbranch_vccnz .LBB0_218
	v_mul_f32_e32 v0, 0xbfb8aa3b, v18
	v_exp_f32_e32 v0, v0
	v_mul_f32_e32 v130, 0xbfb8aa3b, v19
	v_mul_f32_e32 v131, 0xbfb8aa3b, v20
	v_exp_f32_e32 v132, v130
	v_add_f32_e32 v0, 1.0, v0
	v_rcp_f32_e32 v130, v0
	v_exp_f32_e32 v0, v131
	v_mul_f32_e32 v131, 0xbfb8aa3b, v21
	v_exp_f32_e32 v131, v131
	v_add_f32_e32 v140, 1.0, v132
	v_add_f32_e32 v0, 1.0, v0
	v_rcp_f32_e32 v132, v0
	v_add_f32_e32 v0, 1.0, v131
	v_rcp_f32_e32 v133, v0
	v_rcp_f32_e32 v131, v140
	v_pk_mul_f32 v[132:133], v[20:21], v[132:133]
	v_pk_mul_f32 v[130:131], v[18:19], v[130:131]
.LBB0_218:
	v_mov_b32_e32 v140, v154
	v_mov_b32_e32 v141, v154
	v_pk_mul_f32 v[136:137], v[140:141], v[136:137]
	v_pk_mul_f32 v[134:135], v[154:155], v[134:135]
	v_pk_mul_f32 v[132:133], v[140:141], v[132:133]
	v_pk_mul_f32 v[130:131], v[154:155], v[130:131]
	v_cvt_pk_bf16_f32 v134, v134, v135
	v_cvt_pk_bf16_f32 v135, v136, v137
	v_cvt_pk_bf16_f32 v136, v130, v131
	v_cvt_pk_bf16_f32 v137, v132, v133
	ds_bpermute_b32 v134, v200, v134
	ds_bpermute_b32 v135, v200, v135
	ds_bpermute_b32 v136, v200, v136
	ds_bpermute_b32 v137, v200, v137
	s_waitcnt lgkmcnt(0)
	global_store_dwordx4 v[156:157], v[134:137], off offset:256
	v_mov_b64_e32 v[132:133], v[16:17]
	s_and_b64 vcc, exec, s[0:1]
	v_mov_b64_e32 v[130:131], v[14:15]
	s_cbranch_vccnz .LBB0_220
	v_mul_f32_e32 v0, 0xbfb8aa3b, v14
	v_exp_f32_e32 v0, v0
	v_mul_f32_e32 v130, 0xbfb8aa3b, v15
	v_mul_f32_e32 v131, 0xbfb8aa3b, v16
	v_exp_f32_e32 v132, v130
	v_add_f32_e32 v0, 1.0, v0
	v_rcp_f32_e32 v130, v0
	v_exp_f32_e32 v0, v131
	v_mul_f32_e32 v131, 0xbfb8aa3b, v17
	v_exp_f32_e32 v131, v131
	v_add_f32_e32 v134, 1.0, v132
	v_add_f32_e32 v0, 1.0, v0
	v_rcp_f32_e32 v132, v0
	v_add_f32_e32 v0, 1.0, v131
	v_rcp_f32_e32 v133, v0
	v_rcp_f32_e32 v131, v134
	v_pk_mul_f32 v[132:133], v[16:17], v[132:133]
	v_pk_mul_f32 v[130:131], v[14:15], v[130:131]

; DI float siluf(float x) { return x * __builtin_amdgcn_rcpf(1.f + __expf(-x)); }
; template <int EPI>
; DI void gemm_epilogue(const Params& p, int layer, f32x4 (&acc)[2][2][4][2], int brow, int bcol, int pn, int wr, int wc,
;                       int fr, int fq, char* smem, int ksplit = -1) {
;     ...
; #pragma unroll
;       for (int ai = 0; ai < 2; ++ai)
; #pragma unroll
;         for (int m = 0; m < 4; ++m) {
;           __builtin_amdgcn_sched_barrier(0);
;           const int row = brow + ai * 128 + wr * 64 + m * 16 + fr;
; #pragma unroll
;           for (int bj = 0; bj < 2; ++bj) {
;             u32x4 o;
; #pragma unroll
;             for (int n = 0; n < 2; ++n) {
;               f32x4 v = acc[ai][bj][m][n];
;               if (dosilu) {
; #pragma unroll
;                 for (int j = 0; j < 4; ++j) v[j] = siluf(v[j]);
;               }
;               v = v * sc;
;               o[2 * n] = pk_bf16(v[0], v[1]);
;               o[2 * n + 1] = pk_bf16(v[2], v[3]);
;             }
;             *(u32x4*)(Z + (size_t)row * ZW + bcol + bj * 128 + wc * 32 + fq * 8) = o;
;           }
.LBB0_224:
	v_add_u32_e32 v0, 0xb0, v162
	v_mad_i64_i32 v[156:157], s[2:3], v0, s79, v[138:139]
	v_mov_b64_e32 v[140:141], v[4:5]
	s_and_b64 vcc, exec, s[0:1]
	v_mov_b64_e32 v[138:139], v[2:3]
	ds_bpermute_b32 v130, v200, v130
	ds_bpermute_b32 v131, v200, v131
	ds_bpermute_b32 v132, v200, v132
	ds_bpermute_b32 v133, v200, v133
	s_waitcnt lgkmcnt(0)
	global_store_dwordx4 v[156:157], v[130:133], off
	s_cbranch_vccnz .LBB0_226
	v_mul_f32_e32 v0, 0xbfb8aa3b, v2
	v_exp_f32_e32 v0, v0
	v_mul_f32_e32 v130, 0xbfb8aa3b, v3
	v_mul_f32_e32 v131, 0xbfb8aa3b, v4
	v_exp_f32_e32 v132, v130
	v_add_f32_e32 v0, 1.0, v0
	v_rcp_f32_e32 v130, v0
	v_exp_f32_e32 v0, v131
	v_mul_f32_e32 v131, 0xbfb8aa3b, v5
	v_exp_f32_e32 v131, v131
	v_add_f32_e32 v138, 1.0, v132
	v_add_f32_e32 v0, 1.0, v0
	v_rcp_f32_e32 v132, v0
	v_add_f32_e32 v0, 1.0, v131
	v_rcp_f32_e32 v133, v0
	v_rcp_f32_e32 v131, v138
	v_pk_mul_f32 v[140:141], v[4:5], v[132:133]
	v_pk_mul_f32 v[138:139], v[2:3], v[130:131]
.LBB0_226:
	s_nop 0
	v_mov_b32_e32 v132, v154
	v_mov_b32_e32 v133, v154
	v_pk_mul_f32 v[136:137], v[132:133], v[136:137]
	v_pk_mul_f32 v[130:131], v[154:155], v[134:135]
	v_pk_mul_f32 v[134:135], v[154:155], v[138:139]
	v_cvt_pk_bf16_f32 v130, v130, v131
	v_cvt_pk_bf16_f32 v131, v136, v137
	v_pk_mul_f32 v[136:137], v[132:133], v[140:141]
	v_cvt_pk_bf16_f32 v132, v134, v135
	v_cvt_pk_bf16_f32 v133, v136, v137
	ds_bpermute_b32 v130, v200, v130
	ds_bpermute_b32 v131, v200, v131
	ds_bpermute_b32 v132, v200, v132
	ds_bpermute_b32 v133, v200, v133
	s_waitcnt lgkmcnt(0)
	s_andn2_b64 vcc, exec, s[36:37]
	s_mov_b64 s[0:1], -1
	global_store_dwordx4 v[156:157], v[130:133], off offset:256
	s_branch .Lgin_join

; #define BAR __builtin_amdgcn_s_barrier()
;     ...
;     if (!has_next) break;
; #pragma unroll
;     for (int a = 0; a < 2; ++a)
; #pragma unroll
;       for (int b = 0; b < 2; ++b)
; #pragma unroll
;         for (int m = 0; m < 4; ++m)
; #pragma unroll
;           for (int n = 0; n < 2; ++n) acc[a][b][m][n] = (f32x4){0.f, 0.f, 0.f, 0.f};
;     pm = npm; pn = npn; kq = nkq; cA = nA; cB = nB; ++ui;
;     if (wr == 1) BAR;
.Lgin_join:
	s_cbranch_vccnz .LBB0_148
	s_andn2_b64 vcc, exec, s[44:45]
	s_cbranch_vccnz .LBB0_147
	s_barrier
	s_branch .LBB0_147
